# P4 quarter-tile K-loop software-pipelined: one barrier per K-step, next step fragment reads issued before the current MFMAs
# speedup vs baseline: 1.0263x; 1.0263x over previous
; template <class Epi>
; __device__ __forceinline__ void gemm_quarter(LAS unsigned char* lds, const Gemm g, const Unit u, const Epi& E) {
;     const int tid = threadIdx.x, wid = __builtin_amdgcn_readfirstlane(tid >> 6), lane = tid & 63, wr = wid >> 2, wc = wid & 3, fr = lane & 15, fq = lane >> 4;
;     const int K = g.K, nt = K / BK;
;     unsigned voffA[2], voffB[2];
; #pragma unroll
;     for (int i = 0; i < 2; ++i) { int R, C; stage_rc(tid * 16 + i * 8192, R, C); const int Rb = (R & ~31) + perm32(R & 31);
;         voffA[i] = (unsigned)(R * g.lda + C) * 2u; voffB[i] = (unsigned)(Rb * g.ldb + C) * 2u; }
;     const unsigned ldsw = (unsigned)wid * 1024u;
;     const int aoff = lds_byte(wr * 64 + fr, fq * 8), boff = lds_byte(wc * 32 + fr, fq * 8);
;     const char* cA = (const char*)g.A + ((size_t)u.pm * 256 + u.ra) * g.lda * 2; const char* cB = (const char*)g.Bt + ((size_t)u.pn * 256 + u.cb) * g.ldb * 2;
;     f32x4 acc[2][2][4][2];
; #pragma unroll
;     for (int m = 0; m < 4; ++m)
; #pragma unroll
;         for (int n = 0; n < 2; ++n) acc[0][0][m][n] = (f32x4){0.f, 0.f, 0.f, 0.f};
;     ...
;     for (int part = 0; part < Epi::NPART; ++part) {
;         QSTAGE(0, 0); QSTAGE(1, 1); QSTAGE(2, 2);
.LBB0_770:
.LBB0_771:
	s_ashr_i32 s0, s2, 2
	s_addk_i32 s0, 0x200
	s_ashr_i32 s1, s0, 31
	s_lshr_b32 s1, s1, 29
	s_add_i32 s1, s0, s1
	s_ashr_i32 s6, s1, 3
	s_and_b32 s1, s1, -8
	s_sub_i32 s0, s0, s1
	s_cmp_lt_i32 s0, 0
	s_movk_i32 s1, 0x45
	s_cselect_b32 s1, s1, 0x44
	s_mul_i32 s0, s0, s1
	s_add_i32 s26, s0, s6
	s_ashr_i32 s0, s26, 31
	s_lshr_b32 s0, s0, 26
	s_add_i32 s0, s26, s0
	s_ashr_i32 s1, s0, 6
	s_lshl_b32 s27, s1, 3
	s_sub_i32 s1, 0x44, s27
	s_min_u32 s7, s1, 8
	s_and_b32 s35, s0, 0xffffffc0
	s_sub_i32 s8, s26, s35
	v_cvt_f32_ubyte0_e32 v1, s7
	v_cvt_f32_i32_e32 v0, s8
	v_rcp_iflag_f32_e32 v2, v1
	s_ashr_i32 s0, s8, 30
	s_or_b32 s6, s0, 1
	v_bfe_u32 v10, v179, 2, 4
	v_mul_f32_e32 v2, v0, v2
	v_trunc_f32_e32 v2, v2
	v_fma_f32 v0, -v2, v1, v0
	v_cvt_i32_f32_e32 v2, v2
	v_cmp_ge_f32_e64 s[0:1], |v0|, v1
	s_and_b64 s[0:1], s[0:1], exec
	v_lshlrev_b32_e32 v0, 4, v179
	v_and_b32_e32 v1, 32, v179
	s_cselect_b32 s0, s6, 0
	v_readfirstlane_b32 s1, v2
	v_bitop3_b32 v11, v0, v1, 48 bitop3:0x6c
	v_lshrrev_b32_e32 v1, 1, v179
	s_add_i32 s6, s1, s0
	s_lshl_b32 s1, s2, 6
	v_and_b32_e32 v14, 24, v1
	v_lshrrev_b32_e32 v1, 5, v179
	v_bfe_u32 v2, v179, 2, 2
	s_mul_i32 s36, s6, s7
	s_and_b32 s7, s1, 0x80
	s_lshl_b32 s1, s2, 7
	v_and_or_b32 v15, v1, 4, v2
	v_lshrrev_b32_e32 v2, 3, v179
	s_sub_i32 s0, s8, s36
	s_and_b32 s15, s1, 0x80
	v_and_b32_e32 v12, 64, v179
	v_or_b32_e32 v1, v15, v14
	s_movk_i32 s1, 0x70
	v_and_b32_e32 v16, 0x60, v2
	v_add_u32_e32 v17, 0x2000, v0
	s_sext_i32_i8 s0, s0
	v_readfirstlane_b32 s10, v179
	v_or_b32_e32 v13, v11, v12
	v_and_or_b32 v3, v2, s1, v10
	v_or_b32_e32 v2, v1, v16
	v_lshrrev_b32_e32 v0, 7, v17
	s_movk_i32 s1, 0xf0
	s_add_i32 s0, s27, s0
	v_lshl_or_b32 v130, v2, 12, v13
	v_and_or_b32 v2, v0, s1, v10
	s_lshr_b32 s1, s10, 2
	s_and_b32 s37, s1, 0x3fffffc0
	s_ashr_i32 s1, s0, 31
	s_lshr_b32 s11, s10, 1
	s_lshl_b64 s[8:9], s[0:1], 20
	s_add_u32 s20, s18, s8
	s_addc_u32 s21, s19, s9
	s_bfe_i64 s[8:9], s[6:7], 0x80000
	s_lshl_b32 s40, s15, 12
	s_lshl_b64 s[8:9], s[8:9], 20
	s_add_u32 s41, s94, s8
	s_addc_u32 s42, s95, s9
	s_lshl_b32 s1, s10, 4
	s_and_b32 s33, s1, 0xfffffc00
	s_and_b32 s1, s11, 0x60
	s_lshl_b32 s34, s1, 7
	s_lshl_b32 s43, s7, 12
	s_add_u32 s10, s20, s43
	s_addc_u32 s11, s21, 0
	s_add_u32 s20, s41, s40
	v_and_b32_e32 v18, 0xe0, v0
	s_addc_u32 s21, s42, 0
	s_add_i32 s41, s33, 0
	v_lshl_or_b32 v128, v3, 12, v13
	v_or_b32_e32 v0, v1, v18
	s_add_i32 s42, s41, 0x10000
	s_mov_b32 m0, s41
	v_lshl_or_b32 v134, v0, 12, v13
	v_lshlrev_b32_e32 v0, 6, v179
	v_mov_b32_e32 v129, 0
	global_load_lds_dwordx4 v128, s[10:11]
	s_mov_b32 m0, s42
	v_lshl_or_b32 v132, v2, 12, v13
	v_and_b32_e32 v20, 0x3c0, v0
	v_lshlrev_b32_e32 v0, 2, v179
	global_load_lds_dwordx4 v130, s[20:21]
	v_mov_b32_e32 v133, v129
	s_add_i32 m0, s41, 0x2000
	v_and_b32_e32 v21, 32, v0
	v_lshl_add_u64 v[0:1], s[10:11], 0, v[128:129]
	v_mov_b32_e32 v131, v129
	v_lshl_add_u64 v[4:5], s[10:11], 0, v[132:133]
	global_load_lds_dwordx4 v132, s[10:11]
	v_mov_b32_e32 v135, v129
	s_add_i32 m0, s41, 0x12000
	s_mov_b64 s[10:11], 0x80
	v_lshl_add_u64 v[2:3], s[20:21], 0, v[130:131]
	v_lshl_add_u64 v[6:7], s[20:21], 0, v[134:135]
	global_load_lds_dwordx4 v134, s[20:21]
	s_add_i32 m0, s41, 0x4000
	s_add_i32 s20, s41, 0x14000
	v_lshl_add_u64 v[8:9], v[0:1], 0, s[10:11]
	global_load_lds_dwordx4 v[8:9], off
	v_lshl_add_u64 v[8:9], v[2:3], 0, s[10:11]
	s_mov_b32 m0, s20
	s_add_i32 s21, s41, 0x18000
	global_load_lds_dwordx4 v[8:9], off
	v_lshl_add_u64 v[8:9], v[4:5], 0, s[10:11]
	s_add_i32 m0, s41, 0x6000
	v_and_b32_e32 v40, 15, v179
	global_load_lds_dwordx4 v[8:9], off
	v_lshl_add_u64 v[8:9], v[6:7], 0, s[10:11]
	s_add_i32 m0, s41, 0x16000
	s_mov_b64 s[10:11], 0x100
	global_load_lds_dwordx4 v[8:9], off
	s_add_i32 m0, s41, 0x8000
	v_lshl_add_u64 v[0:1], v[0:1], 0, s[10:11]
	global_load_lds_dwordx4 v[0:1], off
	v_lshl_add_u64 v[0:1], v[2:3], 0, s[10:11]
	s_mov_b32 m0, s21
	v_lshl_or_b32 v19, v40, 6, v43
	global_load_lds_dwordx4 v[0:1], off
	v_lshl_add_u64 v[0:1], v[4:5], 0, s[10:11]
	s_add_i32 m0, s41, 0xa000
	s_mov_b32 s20, 0x70000
	global_load_lds_dwordx4 v[0:1], off
	v_lshl_add_u64 v[0:1], v[6:7], 0, s[10:11]
	s_add_i32 m0, s41, 0x1a000
	s_lshl_b32 s10, s37, 7
	global_load_lds_dwordx4 v[0:1], off
	s_add_i32 s10, s10, 0
	v_xad_u32 v46, v19, v21, s10
	s_sub_i32 s10, s26, s36
	s_sub_i32 s10, s10, s35
	s_sext_i32_i8 s10, s10
	s_add_i32 s10, s27, s10
	s_ashr_i32 s11, s10, 31
	s_lshl_b64 s[10:11], s[10:11], 20
	s_or_b32 s10, s10, s43
	v_lshlrev_b32_e32 v0, 9, v179
	v_and_or_b32 v0, v0, s20, v11
	v_lshlrev_b32_e32 v2, 12, v10
	s_add_u32 s10, s68, s10
	v_or3_b32 v0, v0, v2, v12
	v_mov_b32_e32 v1, v129
	s_addc_u32 s11, s69, s11
	v_lshl_add_u64 v[0:1], s[10:11], 0, v[0:1]
	s_mov_b64 s[20:21], 0x16b00180
	v_lshl_add_u64 v[32:33], v[0:1], 0, s[20:21]
	v_lshlrev_b32_e32 v0, 5, v17
	s_mov_b32 s26, 0xf0000
	v_and_or_b32 v0, v0, s26, v11
	v_or3_b32 v0, v0, v2, v12
	v_mov_b32_e32 v1, v129
	v_lshl_add_u64 v[0:1], s[10:11], 0, v[0:1]
	s_or_b32 s8, s8, s40
	v_lshl_add_u64 v[34:35], v[0:1], 0, s[20:21]
	v_or3_b32 v0, v16, v14, v15
	s_add_u32 s8, s68, s8
	v_lshl_or_b32 v0, v0, 12, v13
	v_mov_b32_e32 v1, v129
	s_addc_u32 s9, s69, s9
	v_lshl_add_u64 v[0:1], s[8:9], 0, v[0:1]
	s_mov_b64 s[10:11], 0x3100180
	v_lshl_add_u64 v[36:37], v[0:1], 0, s[10:11]
	v_or3_b32 v0, v18, v14, v15
	v_lshl_or_b32 v0, v0, 12, v13
	v_mov_b32_e32 v1, v129
	v_lshl_add_u64 v[0:1], s[8:9], 0, v[0:1]
	s_mov_b32 s14, 0
	v_or_b32_e32 v44, s37, v40
	v_bitop3_b32 v41, v43, v21, v20 bitop3:0x36
	v_lshl_add_u64 v[38:39], v[0:1], 0, s[10:11]
	s_mov_b32 s35, 0xc000
	s_mov_b64 s[8:9], 0
	v_mov_b32_e32 v28, v129
	v_mov_b32_e32 v29, v129
	v_mov_b32_e32 v30, v129
	v_mov_b32_e32 v31, v129
	v_mov_b32_e32 v24, v129
	v_mov_b32_e32 v25, v129
	v_mov_b32_e32 v26, v129
	v_mov_b32_e32 v27, v129
	v_mov_b32_e32 v20, v129
	v_mov_b32_e32 v21, v129
	v_mov_b32_e32 v22, v129
	v_mov_b32_e32 v23, v129
	v_mov_b32_e32 v16, v129
	v_mov_b32_e32 v17, v129
	v_mov_b32_e32 v18, v129
	v_mov_b32_e32 v19, v129
	v_mov_b32_e32 v12, v129
	v_mov_b32_e32 v13, v129
	v_mov_b32_e32 v14, v129
	v_mov_b32_e32 v15, v129
	v_mov_b32_e32 v8, v129
	v_mov_b32_e32 v9, v129
	v_mov_b32_e32 v10, v129
	v_mov_b32_e32 v11, v129
	v_mov_b32_e32 v0, v129
	v_mov_b32_e32 v1, v129
	v_mov_b32_e32 v2, v129
	v_mov_b32_e32 v3, v129
	v_mov_b32_e32 v4, v129
	v_mov_b32_e32 v5, v129
	v_mov_b32_e32 v6, v129
	v_mov_b32_e32 v7, v129
	v_add_u32_e32 v80, s34, v41
	v_add_u32_e32 v80, 0x10000, v80
	s_mov_b32 s14, 0
	s_waitcnt vmcnt(8)
	s_barrier
; #define LAS __attribute__((address_space(3)))
; template <class Epi>
; __device__ __forceinline__ void gemm_quarter(LAS unsigned char* lds, const Gemm g, const Unit u, const Epi& E) {
;     ...
;         for (int t = 0; t < nt; ++t) {
;             if (t + 3 < nt) { QSTAGE((t + 3) & 3, t + 3); asm volatile("s_waitcnt vmcnt(12)" ::: "memory"); }
;             else if (t + 2 < nt) asm volatile("s_waitcnt vmcnt(8)" ::: "memory");
;             else if (t + 1 < nt) asm volatile("s_waitcnt vmcnt(4)" ::: "memory");
;             else asm volatile("s_waitcnt vmcnt(0)" ::: "memory");
;             __builtin_amdgcn_s_barrier();
;             const int r = t & 3;
;             bf16x8 At[4][2], B0[2][2];
; #pragma unroll
;             for (int m = 0; m < 4; ++m)
; #pragma unroll
;                 for (int k = 0; k < 2; ++k) At[m][k] = *(const LAS bf16x8*)(lds + r * HTB + aoff + m * 2048 + k * 1024);
; #pragma unroll
;             for (int n = 0; n < 2; ++n)
; #pragma unroll
;                 for (int k = 0; k < 2; ++k) B0[n][k] = *(const LAS bf16x8*)(lds + (4 + r) * HTB + boff + n * 2048 + k * 1024);
	s_mov_b32 s11, 0
	v_add_u32_e32 v78, s11, v46
	v_add_u32_e32 v79, s11, v80
	ds_read_b128 v[96:99], v78
	ds_read_b128 v[100:103], v78 offset:1024
	ds_read_b128 v[104:107], v78 offset:2048
	ds_read_b128 v[108:111], v78 offset:3072
	ds_read_b128 v[112:115], v78 offset:4096
	ds_read_b128 v[116:119], v78 offset:5120
	ds_read_b128 v[120:123], v78 offset:6144
	ds_read_b128 v[124:127], v78 offset:7168
	ds_read_b128 v[144:147], v79
	ds_read_b128 v[148:151], v79 offset:1024
	ds_read_b128 v[152:155], v79 offset:2048
	ds_read_b128 v[156:159], v79 offset:3072
.Lq_loop_p4:
	s_add_i32 s35, s14, 2
	s_cmp_lt_u32 s35, 32
	s_cbranch_scc0 .Lq_w0_p4_0
	s_waitcnt vmcnt(4)
	s_branch .Lq_wd_p4_0

; #define LAS __attribute__((address_space(3)))
; template <class Epi>
; __device__ __forceinline__ void gemm_quarter(LAS unsigned char* lds, const Gemm g, const Unit u, const Epi& E) {
;     ...
;         for (int t = 0; t < nt; ++t) {
;             if (t + 3 < nt) { QSTAGE((t + 3) & 3, t + 3); asm volatile("s_waitcnt vmcnt(12)" ::: "memory"); }
;             else if (t + 2 < nt) asm volatile("s_waitcnt vmcnt(8)" ::: "memory");
;             else if (t + 1 < nt) asm volatile("s_waitcnt vmcnt(4)" ::: "memory");
;             else asm volatile("s_waitcnt vmcnt(0)" ::: "memory");
;             __builtin_amdgcn_s_barrier();
;             const int r = t & 3;
;             bf16x8 At[4][2], B0[2][2];
; #pragma unroll
;             for (int m = 0; m < 4; ++m)
; #pragma unroll
;                 for (int k = 0; k < 2; ++k) At[m][k] = *(const LAS bf16x8*)(lds + r * HTB + aoff + m * 2048 + k * 1024);
; #pragma unroll
;             for (int n = 0; n < 2; ++n)
; #pragma unroll
;                 for (int k = 0; k < 2; ++k) B0[n][k] = *(const LAS bf16x8*)(lds + (4 + r) * HTB + boff + n * 2048 + k * 1024);
;             asm volatile("s_waitcnt lgkmcnt(0)" ::: "memory");
; #pragma unroll
;             for (int m = 0; m < 4; ++m)
; #pragma unroll
;                 for (int n = 0; n < 2; ++n)
; #pragma unroll
;                     for (int k = 0; k < 2; ++k) acc[0][0][m][n] = __builtin_amdgcn_mfma_f32_16x16x32_bf16(B0[n][k], At[m][k], acc[0][0][m][n], 0, 0, 0);
;             __builtin_amdgcn_s_barrier();
.Lq_wd_p4_0:
	s_barrier
	s_add_i32 s35, s14, 3
	s_cmp_lt_u32 s35, 32
	s_cbranch_scc0 .Lq_ns_p4_0
	s_add_i32 s10, s14, 3
	s_and_b32 s10, s10, 3
	s_lshl_b32 s10, s10, 14
	s_add_i32 s10, s10, s33
	v_lshl_add_u64 v[74:75], v[32:33], 0, s[8:9]
	s_mov_b32 m0, s10
	s_nop 0
	global_load_lds_dwordx4 v[74:75], off
	v_lshl_add_u64 v[76:77], v[36:37], 0, s[8:9]
	s_add_i32 m0, s10, 0x10000
	s_nop 0
	global_load_lds_dwordx4 v[76:77], off
	v_lshl_add_u64 v[74:75], v[34:35], 0, s[8:9]
	s_add_i32 m0, s10, 0x2000
	s_nop 0
	global_load_lds_dwordx4 v[74:75], off
	v_lshl_add_u64 v[76:77], v[38:39], 0, s[8:9]
	s_add_i32 m0, s10, 0x12000
	s_nop 0
	global_load_lds_dwordx4 v[76:77], off
	s_add_u32 s8, s8, 0x80
	s_addc_u32 s9, s9, 0
.Lq_ns_p4_0:
	s_add_i32 s11, s14, 1
	s_and_b32 s11, s11, 3
	s_lshl_b32 s11, s11, 14
	v_add_u32_e32 v78, s11, v46
	v_add_u32_e32 v79, s11, v80
	ds_read_b128 v[160:163], v78
	ds_read_b128 v[164:167], v78 offset:1024
	ds_read_b128 v[168:171], v78 offset:2048
	ds_read_b128 v[172:175], v78 offset:3072
	ds_read_b128 v[180:183], v78 offset:4096
	ds_read_b128 v[184:187], v78 offset:5120
	ds_read_b128 v[188:191], v78 offset:6144
	ds_read_b128 v[192:195], v78 offset:7168
	ds_read_b128 v[196:199], v79
	ds_read_b128 v[200:203], v79 offset:1024
	ds_read_b128 v[204:207], v79 offset:2048
	ds_read_b128 v[208:211], v79 offset:3072
	s_waitcnt lgkmcnt(12)
	v_mfma_f32_16x16x32_bf16 v[24:27], v[152:155], v[96:99], v[24:27]
	v_mfma_f32_16x16x32_bf16 v[28:31], v[144:147], v[96:99], v[28:31]
	v_mfma_f32_16x16x32_bf16 v[28:31], v[148:151], v[100:103], v[28:31]
	v_mfma_f32_16x16x32_bf16 v[24:27], v[156:159], v[100:103], v[24:27]
	v_mfma_f32_16x16x32_bf16 v[16:19], v[152:155], v[104:107], v[16:19]
	v_mfma_f32_16x16x32_bf16 v[20:23], v[144:147], v[104:107], v[20:23]
	v_mfma_f32_16x16x32_bf16 v[20:23], v[148:151], v[108:111], v[20:23]
	v_mfma_f32_16x16x32_bf16 v[16:19], v[156:159], v[108:111], v[16:19]
	v_mfma_f32_16x16x32_bf16 v[8:11], v[152:155], v[112:115], v[8:11]
	v_mfma_f32_16x16x32_bf16 v[12:15], v[144:147], v[112:115], v[12:15]
	v_mfma_f32_16x16x32_bf16 v[12:15], v[148:151], v[116:119], v[12:15]
	v_mfma_f32_16x16x32_bf16 v[8:11], v[156:159], v[116:119], v[8:11]
	v_mfma_f32_16x16x32_bf16 v[4:7], v[152:155], v[120:123], v[4:7]
	v_mfma_f32_16x16x32_bf16 v[0:3], v[144:147], v[120:123], v[0:3]
	v_mfma_f32_16x16x32_bf16 v[0:3], v[148:151], v[124:127], v[0:3]
	v_mfma_f32_16x16x32_bf16 v[4:7], v[156:159], v[124:127], v[4:7]
	s_add_i32 s14, s14, 1
	s_add_i32 s35, s14, 2
	s_cmp_lt_u32 s35, 32
	s_cbranch_scc0 .Lq_w0_p4_1
	s_waitcnt vmcnt(4)
	s_branch .Lq_wd_p4_1

; #define LAS __attribute__((address_space(3)))
; template <class Epi>
; __device__ __forceinline__ void gemm_quarter(LAS unsigned char* lds, const Gemm g, const Unit u, const Epi& E) {
;     ...
;         for (int t = 0; t < nt; ++t) {
;             if (t + 3 < nt) { QSTAGE((t + 3) & 3, t + 3); asm volatile("s_waitcnt vmcnt(12)" ::: "memory"); }
;             else if (t + 2 < nt) asm volatile("s_waitcnt vmcnt(8)" ::: "memory");
;             else if (t + 1 < nt) asm volatile("s_waitcnt vmcnt(4)" ::: "memory");
;             else asm volatile("s_waitcnt vmcnt(0)" ::: "memory");
;             __builtin_amdgcn_s_barrier();
;             const int r = t & 3;
;             bf16x8 At[4][2], B0[2][2];
; #pragma unroll
;             for (int m = 0; m < 4; ++m)
; #pragma unroll
;                 for (int k = 0; k < 2; ++k) At[m][k] = *(const LAS bf16x8*)(lds + r * HTB + aoff + m * 2048 + k * 1024);
; #pragma unroll
;             for (int n = 0; n < 2; ++n)
; #pragma unroll
;                 for (int k = 0; k < 2; ++k) B0[n][k] = *(const LAS bf16x8*)(lds + (4 + r) * HTB + boff + n * 2048 + k * 1024);
;             asm volatile("s_waitcnt lgkmcnt(0)" ::: "memory");
; #pragma unroll
;             for (int m = 0; m < 4; ++m)
; #pragma unroll
;                 for (int n = 0; n < 2; ++n)
; #pragma unroll
;                     for (int k = 0; k < 2; ++k) acc[0][0][m][n] = __builtin_amdgcn_mfma_f32_16x16x32_bf16(B0[n][k], At[m][k], acc[0][0][m][n], 0, 0, 0);
;             __builtin_amdgcn_s_barrier();
.Lq_wd_p4_1:
	s_add_i32 s35, s14, 1
	s_cmp_lt_u32 s35, 32
	s_cbranch_scc0 .Lq_last_p4
	s_barrier
	s_add_i32 s35, s14, 3
	s_cmp_lt_u32 s35, 32
	s_cbranch_scc0 .Lq_ns_p4_1
	s_add_i32 s10, s14, 3
	s_and_b32 s10, s10, 3
	s_lshl_b32 s10, s10, 14
	s_add_i32 s10, s10, s33
	v_lshl_add_u64 v[74:75], v[32:33], 0, s[8:9]
	s_mov_b32 m0, s10
	s_nop 0
	global_load_lds_dwordx4 v[74:75], off
	v_lshl_add_u64 v[76:77], v[36:37], 0, s[8:9]
	s_add_i32 m0, s10, 0x10000
	s_nop 0
	global_load_lds_dwordx4 v[76:77], off
	v_lshl_add_u64 v[74:75], v[34:35], 0, s[8:9]
	s_add_i32 m0, s10, 0x2000
	s_nop 0
	global_load_lds_dwordx4 v[74:75], off
	v_lshl_add_u64 v[76:77], v[38:39], 0, s[8:9]
	s_add_i32 m0, s10, 0x12000
	s_nop 0
	global_load_lds_dwordx4 v[76:77], off
	s_add_u32 s8, s8, 0x80
	s_addc_u32 s9, s9, 0
.Lq_ns_p4_1:
	s_add_i32 s11, s14, 1
	s_and_b32 s11, s11, 3
	s_lshl_b32 s11, s11, 14
	v_add_u32_e32 v78, s11, v46
	v_add_u32_e32 v79, s11, v80
	ds_read_b128 v[96:99], v78
	ds_read_b128 v[100:103], v78 offset:1024
	ds_read_b128 v[104:107], v78 offset:2048
	ds_read_b128 v[108:111], v78 offset:3072
	ds_read_b128 v[112:115], v78 offset:4096
	ds_read_b128 v[116:119], v78 offset:5120
	ds_read_b128 v[120:123], v78 offset:6144
	ds_read_b128 v[124:127], v78 offset:7168
	ds_read_b128 v[144:147], v79
	ds_read_b128 v[148:151], v79 offset:1024
	ds_read_b128 v[152:155], v79 offset:2048
	ds_read_b128 v[156:159], v79 offset:3072
	s_waitcnt lgkmcnt(12)
	v_mfma_f32_16x16x32_bf16 v[24:27], v[204:207], v[160:163], v[24:27]
	v_mfma_f32_16x16x32_bf16 v[28:31], v[196:199], v[160:163], v[28:31]
	v_mfma_f32_16x16x32_bf16 v[28:31], v[200:203], v[164:167], v[28:31]
	v_mfma_f32_16x16x32_bf16 v[24:27], v[208:211], v[164:167], v[24:27]
	v_mfma_f32_16x16x32_bf16 v[16:19], v[204:207], v[168:171], v[16:19]
	v_mfma_f32_16x16x32_bf16 v[20:23], v[196:199], v[168:171], v[20:23]
	v_mfma_f32_16x16x32_bf16 v[20:23], v[200:203], v[172:175], v[20:23]
	v_mfma_f32_16x16x32_bf16 v[16:19], v[208:211], v[172:175], v[16:19]
	v_mfma_f32_16x16x32_bf16 v[8:11], v[204:207], v[180:183], v[8:11]
	v_mfma_f32_16x16x32_bf16 v[12:15], v[196:199], v[180:183], v[12:15]
	v_mfma_f32_16x16x32_bf16 v[12:15], v[200:203], v[184:187], v[12:15]
	v_mfma_f32_16x16x32_bf16 v[8:11], v[208:211], v[184:187], v[8:11]
	v_mfma_f32_16x16x32_bf16 v[4:7], v[204:207], v[188:191], v[4:7]
	v_mfma_f32_16x16x32_bf16 v[0:3], v[196:199], v[188:191], v[0:3]
	v_mfma_f32_16x16x32_bf16 v[0:3], v[200:203], v[192:195], v[0:3]
	v_mfma_f32_16x16x32_bf16 v[4:7], v[208:211], v[192:195], v[4:7]
	s_add_i32 s14, s14, 1
	s_branch .Lq_loop_p4
.Lq_last_p4:
	s_waitcnt lgkmcnt(0)
	s_barrier
	v_mfma_f32_16x16x32_bf16 v[24:27], v[204:207], v[160:163], v[24:27]
	v_mfma_f32_16x16x32_bf16 v[28:31], v[196:199], v[160:163], v[28:31]
	v_mfma_f32_16x16x32_bf16 v[28:31], v[200:203], v[164:167], v[28:31]
	v_mfma_f32_16x16x32_bf16 v[24:27], v[208:211], v[164:167], v[24:27]
	v_mfma_f32_16x16x32_bf16 v[16:19], v[204:207], v[168:171], v[16:19]
	v_mfma_f32_16x16x32_bf16 v[20:23], v[196:199], v[168:171], v[20:23]
	v_mfma_f32_16x16x32_bf16 v[20:23], v[200:203], v[172:175], v[20:23]
	v_mfma_f32_16x16x32_bf16 v[16:19], v[208:211], v[172:175], v[16:19]
	v_mfma_f32_16x16x32_bf16 v[8:11], v[204:207], v[180:183], v[8:11]
	v_mfma_f32_16x16x32_bf16 v[12:15], v[196:199], v[180:183], v[12:15]
	v_mfma_f32_16x16x32_bf16 v[12:15], v[200:203], v[184:187], v[12:15]
	v_mfma_f32_16x16x32_bf16 v[8:11], v[208:211], v[184:187], v[8:11]
	v_mfma_f32_16x16x32_bf16 v[4:7], v[204:207], v[188:191], v[4:7]
	v_mfma_f32_16x16x32_bf16 v[0:3], v[196:199], v[188:191], v[0:3]
	v_mfma_f32_16x16x32_bf16 v[0:3], v[200:203], v[192:195], v[0:3]
	v_mfma_f32_16x16x32_bf16 v[4:7], v[208:211], v[192:195], v[4:7]
